# baseline (speedup 1.0000x reference)
.LBB0_187:
	s_add_u32 m0, s35, 0xc000
	ds_read_b128 v[176:179], v164
	ds_read_b128 v[180:183], v164 offset:1024
	ds_read_b128 v[184:187], v164 offset:2048
	ds_read_b128 v[188:191], v164 offset:3072
	ds_read_b128 v[192:195], v162
	ds_read_b128 v[196:199], v162 offset:1024
	ds_read_b128 v[200:203], v162 offset:2048
	ds_read_b128 v[204:207], v162 offset:3072
	ds_read_b128 v[208:211], v162 offset:4096
	ds_read_b128 v[212:215], v162 offset:5120
	ds_read_b128 v[216:219], v162 offset:6144
	ds_read_b128 v[220:223], v162 offset:7168
	global_load_lds_dwordx4 v128, s[76:77]
	s_add_u32 m0, s35, 0xe000
	s_nop 0
	global_load_lds_dwordx4 v130, s[76:77]
	s_add_u32 s76, s76, 0x80
	s_addc_u32 s77, s77, 0
	s_waitcnt lgkmcnt(8)
	s_barrier
	s_waitcnt lgkmcnt(0)
	v_mfma_f32_16x16x32_bf16 v[124:127], v[176:179], v[192:195], v[124:127]
	v_mfma_f32_16x16x32_bf16 v[120:123], v[184:187], v[192:195], v[120:123]
	v_mfma_f32_16x16x32_bf16 v[116:119], v[176:179], v[200:203], v[116:119]
	v_mfma_f32_16x16x32_bf16 v[112:115], v[184:187], v[200:203], v[112:115]
	v_mfma_f32_16x16x32_bf16 v[108:111], v[176:179], v[208:211], v[108:111]
	v_mfma_f32_16x16x32_bf16 v[104:107], v[184:187], v[208:211], v[104:107]
	v_mfma_f32_16x16x32_bf16 v[100:103], v[176:179], v[216:219], v[100:103]
	v_mfma_f32_16x16x32_bf16 v[96:99], v[184:187], v[216:219], v[96:99]
	v_mfma_f32_16x16x32_bf16 v[124:127], v[180:183], v[196:199], v[124:127]
	v_mfma_f32_16x16x32_bf16 v[120:123], v[188:191], v[196:199], v[120:123]
	v_mfma_f32_16x16x32_bf16 v[116:119], v[180:183], v[204:207], v[116:119]
	v_mfma_f32_16x16x32_bf16 v[112:115], v[188:191], v[204:207], v[112:115]
	v_mfma_f32_16x16x32_bf16 v[108:111], v[180:183], v[212:215], v[108:111]
	v_mfma_f32_16x16x32_bf16 v[104:107], v[188:191], v[212:215], v[104:107]
	v_mfma_f32_16x16x32_bf16 v[100:103], v[180:183], v[220:223], v[100:103]
	v_mfma_f32_16x16x32_bf16 v[96:99], v[188:191], v[220:223], v[96:99]
	s_barrier
	s_add_u32 m0, s35, 0x10000
	ds_read_b128 v[224:227], v164 offset:16384
	ds_read_b128 v[228:231], v164 offset:17408
	ds_read_b128 v[232:235], v164 offset:18432
	ds_read_b128 v[236:239], v164 offset:19456
	global_load_lds_dwordx4 v128, s[42:43]
	s_add_u32 m0, s35, 0x12000
	s_nop 0
	global_load_lds_dwordx4 v130, s[42:43]
	s_add_u32 s42, s42, 0x80
	s_addc_u32 s43, s43, 0
	s_add_i32 s34, s34, 2
	s_barrier
	s_waitcnt lgkmcnt(0)
	v_mfma_f32_16x16x32_bf16 v[92:95], v[224:227], v[192:195], v[92:95]
	v_mfma_f32_16x16x32_bf16 v[88:91], v[232:235], v[192:195], v[88:91]
	v_mfma_f32_16x16x32_bf16 v[84:87], v[224:227], v[200:203], v[84:87]
	v_mfma_f32_16x16x32_bf16 v[80:83], v[232:235], v[200:203], v[80:83]
	v_mfma_f32_16x16x32_bf16 v[76:79], v[224:227], v[208:211], v[76:79]
	v_mfma_f32_16x16x32_bf16 v[72:75], v[232:235], v[208:211], v[72:75]
	v_mfma_f32_16x16x32_bf16 v[68:71], v[224:227], v[216:219], v[68:71]
	v_mfma_f32_16x16x32_bf16 v[64:67], v[232:235], v[216:219], v[64:67]
	v_mfma_f32_16x16x32_bf16 v[92:95], v[228:231], v[196:199], v[92:95]
	v_mfma_f32_16x16x32_bf16 v[88:91], v[236:239], v[196:199], v[88:91]
	v_mfma_f32_16x16x32_bf16 v[84:87], v[228:231], v[204:207], v[84:87]
	v_mfma_f32_16x16x32_bf16 v[80:83], v[236:239], v[204:207], v[80:83]
	v_mfma_f32_16x16x32_bf16 v[76:79], v[228:231], v[212:215], v[76:79]
	v_mfma_f32_16x16x32_bf16 v[72:75], v[236:239], v[212:215], v[72:75]
	v_mfma_f32_16x16x32_bf16 v[68:71], v[228:231], v[220:223], v[68:71]
	v_mfma_f32_16x16x32_bf16 v[64:67], v[236:239], v[220:223], v[64:67]
	s_barrier
	s_add_u32 m0, s35, 0x0
	ds_read_b128 v[192:195], v162 offset:16384
	ds_read_b128 v[196:199], v162 offset:17408
	ds_read_b128 v[200:203], v162 offset:18432
	ds_read_b128 v[204:207], v162 offset:19456
	ds_read_b128 v[208:211], v162 offset:20480
	ds_read_b128 v[212:215], v162 offset:21504
	ds_read_b128 v[216:219], v162 offset:22528
	ds_read_b128 v[220:223], v162 offset:23552
	global_load_lds_dwordx4 v128, s[72:73]
	s_add_u32 m0, s35, 0x2000
	s_nop 0
	global_load_lds_dwordx4 v130, s[72:73]
	s_add_u32 s72, s72, 0x80
	s_addc_u32 s73, s73, 0
	s_barrier
	s_waitcnt lgkmcnt(0)
	v_mfma_f32_16x16x32_bf16 v[60:63], v[176:179], v[192:195], v[60:63]
	v_mfma_f32_16x16x32_bf16 v[56:59], v[184:187], v[192:195], v[56:59]
	v_mfma_f32_16x16x32_bf16 v[52:55], v[176:179], v[200:203], v[52:55]
	v_mfma_f32_16x16x32_bf16 v[48:51], v[184:187], v[200:203], v[48:51]
	v_mfma_f32_16x16x32_bf16 v[44:47], v[176:179], v[208:211], v[44:47]
	v_mfma_f32_16x16x32_bf16 v[40:43], v[184:187], v[208:211], v[40:43]
	v_mfma_f32_16x16x32_bf16 v[36:39], v[176:179], v[216:219], v[36:39]
	v_mfma_f32_16x16x32_bf16 v[32:35], v[184:187], v[216:219], v[32:35]
	v_mfma_f32_16x16x32_bf16 v[60:63], v[180:183], v[196:199], v[60:63]
	v_mfma_f32_16x16x32_bf16 v[56:59], v[188:191], v[196:199], v[56:59]
	v_mfma_f32_16x16x32_bf16 v[52:55], v[180:183], v[204:207], v[52:55]
	v_mfma_f32_16x16x32_bf16 v[48:51], v[188:191], v[204:207], v[48:51]
	v_mfma_f32_16x16x32_bf16 v[44:47], v[180:183], v[212:215], v[44:47]
	v_mfma_f32_16x16x32_bf16 v[40:43], v[188:191], v[212:215], v[40:43]
	v_mfma_f32_16x16x32_bf16 v[36:39], v[180:183], v[220:223], v[36:39]
	v_mfma_f32_16x16x32_bf16 v[32:35], v[188:191], v[220:223], v[32:35]
	s_barrier
	s_add_u32 m0, s35, 0x14000
	s_nop 0
	global_load_lds_dwordx4 v128, s[78:79]
	s_add_u32 m0, s35, 0x16000
	s_nop 0
	global_load_lds_dwordx4 v130, s[78:79]
	s_add_u32 s78, s78, 0x80
	s_addc_u32 s79, s79, 0
	s_waitcnt vmcnt(6)
	s_barrier
	v_mfma_f32_16x16x32_bf16 v[28:31], v[224:227], v[192:195], v[28:31]
	v_mfma_f32_16x16x32_bf16 v[24:27], v[232:235], v[192:195], v[24:27]
	v_mfma_f32_16x16x32_bf16 v[20:23], v[224:227], v[200:203], v[20:23]
	v_mfma_f32_16x16x32_bf16 v[16:19], v[232:235], v[200:203], v[16:19]
	v_mfma_f32_16x16x32_bf16 v[12:15], v[224:227], v[208:211], v[12:15]
	v_mfma_f32_16x16x32_bf16 v[8:11], v[232:235], v[208:211], v[8:11]
	v_mfma_f32_16x16x32_bf16 v[4:7], v[224:227], v[216:219], v[4:7]
	v_mfma_f32_16x16x32_bf16 v[0:3], v[232:235], v[216:219], v[0:3]
	v_mfma_f32_16x16x32_bf16 v[28:31], v[228:231], v[196:199], v[28:31]
	v_mfma_f32_16x16x32_bf16 v[24:27], v[236:239], v[196:199], v[24:27]
	v_mfma_f32_16x16x32_bf16 v[20:23], v[228:231], v[204:207], v[20:23]
	v_mfma_f32_16x16x32_bf16 v[16:19], v[236:239], v[204:207], v[16:19]
	v_mfma_f32_16x16x32_bf16 v[12:15], v[228:231], v[212:215], v[12:15]
	v_mfma_f32_16x16x32_bf16 v[8:11], v[236:239], v[212:215], v[8:11]
	v_mfma_f32_16x16x32_bf16 v[4:7], v[228:231], v[220:223], v[4:7]
	v_mfma_f32_16x16x32_bf16 v[0:3], v[236:239], v[220:223], v[0:3]
	s_barrier
	s_add_u32 m0, s35, 0x4000
	ds_read_b128 v[176:179], v164 offset:32768
	ds_read_b128 v[180:183], v164 offset:33792
	ds_read_b128 v[184:187], v164 offset:34816
	ds_read_b128 v[188:191], v164 offset:35840
	ds_read_b128 v[192:195], v162 offset:32768
	ds_read_b128 v[196:199], v162 offset:33792
	ds_read_b128 v[200:203], v162 offset:34816
	ds_read_b128 v[204:207], v162 offset:35840
	ds_read_b128 v[208:211], v162 offset:36864
	ds_read_b128 v[212:215], v162 offset:37888
	ds_read_b128 v[216:219], v162 offset:38912
	ds_read_b128 v[220:223], v162 offset:39936
	global_load_lds_dwordx4 v128, s[76:77]
	s_add_u32 m0, s35, 0x6000
	s_nop 0
	global_load_lds_dwordx4 v130, s[76:77]
	s_add_u32 s76, s76, 0x80
	s_addc_u32 s77, s77, 0
	s_waitcnt lgkmcnt(8)
	s_barrier
	s_waitcnt lgkmcnt(0)
	v_mfma_f32_16x16x32_bf16 v[124:127], v[176:179], v[192:195], v[124:127]
	v_mfma_f32_16x16x32_bf16 v[120:123], v[184:187], v[192:195], v[120:123]
	v_mfma_f32_16x16x32_bf16 v[116:119], v[176:179], v[200:203], v[116:119]
	v_mfma_f32_16x16x32_bf16 v[112:115], v[184:187], v[200:203], v[112:115]
	v_mfma_f32_16x16x32_bf16 v[108:111], v[176:179], v[208:211], v[108:111]
	v_mfma_f32_16x16x32_bf16 v[104:107], v[184:187], v[208:211], v[104:107]
	v_mfma_f32_16x16x32_bf16 v[100:103], v[176:179], v[216:219], v[100:103]
	v_mfma_f32_16x16x32_bf16 v[96:99], v[184:187], v[216:219], v[96:99]
	v_mfma_f32_16x16x32_bf16 v[124:127], v[180:183], v[196:199], v[124:127]
	v_mfma_f32_16x16x32_bf16 v[120:123], v[188:191], v[196:199], v[120:123]
	v_mfma_f32_16x16x32_bf16 v[116:119], v[180:183], v[204:207], v[116:119]
	v_mfma_f32_16x16x32_bf16 v[112:115], v[188:191], v[204:207], v[112:115]
	v_mfma_f32_16x16x32_bf16 v[108:111], v[180:183], v[212:215], v[108:111]
	v_mfma_f32_16x16x32_bf16 v[104:107], v[188:191], v[212:215], v[104:107]
	v_mfma_f32_16x16x32_bf16 v[100:103], v[180:183], v[220:223], v[100:103]
	v_mfma_f32_16x16x32_bf16 v[96:99], v[188:191], v[220:223], v[96:99]
	s_barrier
	s_add_u32 m0, s35, 0x18000
	ds_read_b128 v[224:227], v164 offset:49152
	ds_read_b128 v[228:231], v164 offset:50176
	ds_read_b128 v[232:235], v164 offset:51200
	ds_read_b128 v[236:239], v164 offset:52224
	global_load_lds_dwordx4 v128, s[42:43]
	s_add_u32 m0, s35, 0x1a000
	s_nop 0
	global_load_lds_dwordx4 v130, s[42:43]
	s_add_u32 s42, s42, 0x80
	s_addc_u32 s43, s43, 0
	s_barrier
	s_waitcnt lgkmcnt(0)
	v_mfma_f32_16x16x32_bf16 v[92:95], v[224:227], v[192:195], v[92:95]
	v_mfma_f32_16x16x32_bf16 v[88:91], v[232:235], v[192:195], v[88:91]
	v_mfma_f32_16x16x32_bf16 v[84:87], v[224:227], v[200:203], v[84:87]
	v_mfma_f32_16x16x32_bf16 v[80:83], v[232:235], v[200:203], v[80:83]
	v_mfma_f32_16x16x32_bf16 v[76:79], v[224:227], v[208:211], v[76:79]
	v_mfma_f32_16x16x32_bf16 v[72:75], v[232:235], v[208:211], v[72:75]
	v_mfma_f32_16x16x32_bf16 v[68:71], v[224:227], v[216:219], v[68:71]
	v_mfma_f32_16x16x32_bf16 v[64:67], v[232:235], v[216:219], v[64:67]
	v_mfma_f32_16x16x32_bf16 v[92:95], v[228:231], v[196:199], v[92:95]
	v_mfma_f32_16x16x32_bf16 v[88:91], v[236:239], v[196:199], v[88:91]
	v_mfma_f32_16x16x32_bf16 v[84:87], v[228:231], v[204:207], v[84:87]
	v_mfma_f32_16x16x32_bf16 v[80:83], v[236:239], v[204:207], v[80:83]
	v_mfma_f32_16x16x32_bf16 v[76:79], v[228:231], v[212:215], v[76:79]
	v_mfma_f32_16x16x32_bf16 v[72:75], v[236:239], v[212:215], v[72:75]
	v_mfma_f32_16x16x32_bf16 v[68:71], v[228:231], v[220:223], v[68:71]
	v_mfma_f32_16x16x32_bf16 v[64:67], v[236:239], v[220:223], v[64:67]
	s_barrier
	s_add_u32 m0, s35, 0x8000
	ds_read_b128 v[192:195], v162 offset:49152
	ds_read_b128 v[196:199], v162 offset:50176
	ds_read_b128 v[200:203], v162 offset:51200
	ds_read_b128 v[204:207], v162 offset:52224
	ds_read_b128 v[208:211], v162 offset:53248
	ds_read_b128 v[212:215], v162 offset:54272
	ds_read_b128 v[216:219], v162 offset:55296
	ds_read_b128 v[220:223], v162 offset:56320
	global_load_lds_dwordx4 v128, s[72:73]
	s_add_u32 m0, s35, 0xa000
	s_nop 0
	global_load_lds_dwordx4 v130, s[72:73]
	s_add_u32 s72, s72, 0x80
	s_addc_u32 s73, s73, 0
	s_barrier
	s_waitcnt lgkmcnt(0)
	v_mfma_f32_16x16x32_bf16 v[60:63], v[176:179], v[192:195], v[60:63]
	v_mfma_f32_16x16x32_bf16 v[56:59], v[184:187], v[192:195], v[56:59]
	v_mfma_f32_16x16x32_bf16 v[52:55], v[176:179], v[200:203], v[52:55]
	v_mfma_f32_16x16x32_bf16 v[48:51], v[184:187], v[200:203], v[48:51]
	v_mfma_f32_16x16x32_bf16 v[44:47], v[176:179], v[208:211], v[44:47]
	v_mfma_f32_16x16x32_bf16 v[40:43], v[184:187], v[208:211], v[40:43]
	v_mfma_f32_16x16x32_bf16 v[36:39], v[176:179], v[216:219], v[36:39]
	v_mfma_f32_16x16x32_bf16 v[32:35], v[184:187], v[216:219], v[32:35]
	v_mfma_f32_16x16x32_bf16 v[60:63], v[180:183], v[196:199], v[60:63]
	v_mfma_f32_16x16x32_bf16 v[56:59], v[188:191], v[196:199], v[56:59]
	v_mfma_f32_16x16x32_bf16 v[52:55], v[180:183], v[204:207], v[52:55]
	v_mfma_f32_16x16x32_bf16 v[48:51], v[188:191], v[204:207], v[48:51]
	v_mfma_f32_16x16x32_bf16 v[44:47], v[180:183], v[212:215], v[44:47]
	v_mfma_f32_16x16x32_bf16 v[40:43], v[188:191], v[212:215], v[40:43]
	v_mfma_f32_16x16x32_bf16 v[36:39], v[180:183], v[220:223], v[36:39]
	v_mfma_f32_16x16x32_bf16 v[32:35], v[188:191], v[220:223], v[32:35]
	s_barrier
	s_add_u32 m0, s35, 0x1c000
	s_nop 0
	global_load_lds_dwordx4 v128, s[78:79]
	s_add_u32 m0, s35, 0x1e000
	s_nop 0
	global_load_lds_dwordx4 v130, s[78:79]
	s_add_u32 s78, s78, 0x80
	s_addc_u32 s79, s79, 0
	s_waitcnt vmcnt(6)
	s_barrier
	v_mfma_f32_16x16x32_bf16 v[28:31], v[224:227], v[192:195], v[28:31]
	v_mfma_f32_16x16x32_bf16 v[24:27], v[232:235], v[192:195], v[24:27]
	v_mfma_f32_16x16x32_bf16 v[20:23], v[224:227], v[200:203], v[20:23]
	v_mfma_f32_16x16x32_bf16 v[16:19], v[232:235], v[200:203], v[16:19]
	v_mfma_f32_16x16x32_bf16 v[12:15], v[224:227], v[208:211], v[12:15]
	v_mfma_f32_16x16x32_bf16 v[8:11], v[232:235], v[208:211], v[8:11]
	v_mfma_f32_16x16x32_bf16 v[4:7], v[224:227], v[216:219], v[4:7]
	v_mfma_f32_16x16x32_bf16 v[0:3], v[232:235], v[216:219], v[0:3]
	v_mfma_f32_16x16x32_bf16 v[28:31], v[228:231], v[196:199], v[28:31]
	v_mfma_f32_16x16x32_bf16 v[24:27], v[236:239], v[196:199], v[24:27]
	v_mfma_f32_16x16x32_bf16 v[20:23], v[228:231], v[204:207], v[20:23]
	v_mfma_f32_16x16x32_bf16 v[16:19], v[236:239], v[204:207], v[16:19]
	v_mfma_f32_16x16x32_bf16 v[12:15], v[228:231], v[212:215], v[12:15]
	v_mfma_f32_16x16x32_bf16 v[8:11], v[236:239], v[212:215], v[8:11]
	v_mfma_f32_16x16x32_bf16 v[4:7], v[228:231], v[220:223], v[4:7]
	v_mfma_f32_16x16x32_bf16 v[0:3], v[236:239], v[220:223], v[0:3]
	s_cmp_lt_u32 s34, s3
	s_barrier
	s_cbranch_scc1 .LBB0_187
	s_mov_b64 s[72:73], 0x80
	s_mov_b64 s[76:77], 0x100
	s_mov_b64 s[78:79], 0x180
	s_add_i32 s66, s2, -1
	s_lshl_b64 s[2:3], s[66:67], 7
	s_add_u32 s2, s54, s2
	s_addc_u32 s3, s55, s3
	v_readfirstlane_b32 s34, v174
	v_lshl_add_u64 v[150:151], s[2:3], 0, v[128:129]
	s_mov_b32 m0, s34
	v_lshl_add_u64 v[130:131], s[2:3], 0, v[130:131]
	v_readfirstlane_b32 s2, v175
	ds_read_b128 v[132:135], v164
	ds_read_b128 v[136:139], v164 offset:1024
	ds_read_b128 v[140:143], v164 offset:2048
	ds_read_b128 v[144:147], v164 offset:3072
	ds_read_b128 v[158:161], v162
	ds_read_b128 v[166:169], v162 offset:1024
	ds_read_b128 v[170:173], v162 offset:2048
	ds_read_b128 v[176:179], v162 offset:3072
	ds_read_b128 v[180:183], v162 offset:4096
	ds_read_b128 v[184:187], v162 offset:5120
	ds_read_b128 v[188:191], v162 offset:6144
	ds_read_b128 v[192:195], v162 offset:7168
	global_load_lds_dwordx4 v[150:151], off
	s_mov_b32 m0, s2
	s_nop 0
	global_load_lds_dwordx4 v[130:131], off
	s_barrier
	s_waitcnt lgkmcnt(0)
	s_setprio 1
	s_waitcnt lgkmcnt(0)
	v_mfma_f32_16x16x32_bf16 v[124:127], v[132:135], v[158:161], v[124:127]
	v_mfma_f32_16x16x32_bf16 v[120:123], v[140:143], v[158:161], v[120:123]
	v_mfma_f32_16x16x32_bf16 v[116:119], v[132:135], v[170:173], v[116:119]
	v_mfma_f32_16x16x32_bf16 v[112:115], v[140:143], v[170:173], v[112:115]
	v_mfma_f32_16x16x32_bf16 v[100:103], v[132:135], v[188:191], v[100:103]
	v_mfma_f32_16x16x32_bf16 v[96:99], v[140:143], v[188:191], v[96:99]
	v_mfma_f32_16x16x32_bf16 v[124:127], v[136:139], v[166:169], v[124:127]
	v_mfma_f32_16x16x32_bf16 v[120:123], v[144:147], v[166:169], v[120:123]
	v_mfma_f32_16x16x32_bf16 v[116:119], v[136:139], v[176:179], v[116:119]
	v_mfma_f32_16x16x32_bf16 v[112:115], v[144:147], v[176:179], v[112:115]
	v_mfma_f32_16x16x32_bf16 v[108:111], v[132:135], v[180:183], v[108:111]
	v_mfma_f32_16x16x32_bf16 v[104:107], v[140:143], v[180:183], v[104:107]
	v_mfma_f32_16x16x32_bf16 v[100:103], v[136:139], v[192:195], v[100:103]
	v_mfma_f32_16x16x32_bf16 v[96:99], v[144:147], v[192:195], v[96:99]
	v_mfma_f32_16x16x32_bf16 v[196:199], v[136:139], v[184:187], v[108:111]
	v_mfma_f32_16x16x32_bf16 v[200:203], v[144:147], v[184:187], v[104:107]
	s_setprio 0
	s_barrier
	s_nop 1
	ds_read_b128 v[104:107], v164 offset:16384
	ds_read_b128 v[108:111], v164 offset:17408
	ds_read_b128 v[204:207], v164 offset:18432
	ds_read_b128 v[208:211], v164 offset:19456
	s_barrier
	s_waitcnt lgkmcnt(0)
	s_setprio 1
	s_waitcnt lgkmcnt(0)
	v_mfma_f32_16x16x32_bf16 v[84:87], v[104:107], v[170:173], v[84:87]
	v_mfma_f32_16x16x32_bf16 v[80:83], v[204:207], v[170:173], v[80:83]
	v_mfma_f32_16x16x32_bf16 v[68:71], v[104:107], v[188:191], v[68:71]
	v_mfma_f32_16x16x32_bf16 v[64:67], v[204:207], v[188:191], v[64:67]
	v_mfma_f32_16x16x32_bf16 v[92:95], v[104:107], v[158:161], v[92:95]
	v_mfma_f32_16x16x32_bf16 v[88:91], v[204:207], v[158:161], v[88:91]
	v_mfma_f32_16x16x32_bf16 v[84:87], v[108:111], v[176:179], v[84:87]
	v_mfma_f32_16x16x32_bf16 v[80:83], v[208:211], v[176:179], v[80:83]
	v_mfma_f32_16x16x32_bf16 v[76:79], v[104:107], v[180:183], v[76:79]
	v_mfma_f32_16x16x32_bf16 v[72:75], v[204:207], v[180:183], v[72:75]
	v_mfma_f32_16x16x32_bf16 v[68:71], v[108:111], v[192:195], v[68:71]
	v_mfma_f32_16x16x32_bf16 v[64:67], v[208:211], v[192:195], v[64:67]
	v_mfma_f32_16x16x32_bf16 v[212:215], v[108:111], v[166:169], v[92:95]
	v_mfma_f32_16x16x32_bf16 v[158:161], v[208:211], v[166:169], v[88:91]
	v_mfma_f32_16x16x32_bf16 v[166:169], v[108:111], v[184:187], v[76:79]
	v_mfma_f32_16x16x32_bf16 v[170:173], v[208:211], v[184:187], v[72:75]
	s_setprio 0
	s_barrier
	s_nop 0
	ds_read_b128 v[72:75], v162 offset:16384
	ds_read_b128 v[76:79], v162 offset:17408
	ds_read_b128 v[88:91], v162 offset:18432
	ds_read_b128 v[92:95], v162 offset:19456
	ds_read_b128 v[174:177], v162 offset:20480
	ds_read_b128 v[178:181], v162 offset:21504
	ds_read_b128 v[182:185], v162 offset:22528
	ds_read_b128 v[186:189], v162 offset:23552
	s_waitcnt vmcnt(4)
	s_barrier
	s_waitcnt lgkmcnt(0)
	s_setprio 1
	s_waitcnt lgkmcnt(0)
	v_mfma_f32_16x16x32_bf16 v[60:63], v[132:135], v[72:75], v[60:63]
	v_mfma_f32_16x16x32_bf16 v[56:59], v[140:143], v[72:75], v[56:59]
	v_mfma_f32_16x16x32_bf16 v[52:55], v[132:135], v[88:91], v[52:55]
	v_mfma_f32_16x16x32_bf16 v[48:51], v[140:143], v[88:91], v[48:51]
	v_mfma_f32_16x16x32_bf16 v[36:39], v[132:135], v[182:185], v[36:39]
	v_mfma_f32_16x16x32_bf16 v[32:35], v[140:143], v[182:185], v[32:35]
	v_mfma_f32_16x16x32_bf16 v[60:63], v[136:139], v[76:79], v[60:63]
	v_mfma_f32_16x16x32_bf16 v[56:59], v[144:147], v[76:79], v[56:59]
	v_mfma_f32_16x16x32_bf16 v[52:55], v[136:139], v[92:95], v[52:55]
	v_mfma_f32_16x16x32_bf16 v[48:51], v[144:147], v[92:95], v[48:51]
	v_mfma_f32_16x16x32_bf16 v[44:47], v[132:135], v[174:177], v[44:47]
	v_mfma_f32_16x16x32_bf16 v[40:43], v[140:143], v[174:177], v[40:43]
	v_mfma_f32_16x16x32_bf16 v[36:39], v[136:139], v[186:189], v[36:39]
	v_mfma_f32_16x16x32_bf16 v[32:35], v[144:147], v[186:189], v[32:35]
	v_mfma_f32_16x16x32_bf16 v[190:193], v[136:139], v[178:181], v[44:47]
	v_mfma_f32_16x16x32_bf16 v[216:219], v[144:147], v[178:181], v[40:43]
	s_setprio 0
	s_setprio 1
	v_mfma_f32_16x16x32_bf16 v[20:23], v[104:107], v[88:91], v[20:23]
	v_mfma_f32_16x16x32_bf16 v[16:19], v[204:207], v[88:91], v[16:19]
	v_mfma_f32_16x16x32_bf16 v[4:7], v[104:107], v[182:185], v[4:7]
	v_mfma_f32_16x16x32_bf16 v[0:3], v[204:207], v[182:185], v[0:3]
	v_mfma_f32_16x16x32_bf16 v[28:31], v[104:107], v[72:75], v[28:31]
	v_mfma_f32_16x16x32_bf16 v[24:27], v[204:207], v[72:75], v[24:27]
	v_mfma_f32_16x16x32_bf16 v[20:23], v[108:111], v[92:95], v[20:23]
	v_mfma_f32_16x16x32_bf16 v[16:19], v[208:211], v[92:95], v[16:19]
	v_mfma_f32_16x16x32_bf16 v[12:15], v[104:107], v[174:177], v[12:15]
	v_mfma_f32_16x16x32_bf16 v[8:11], v[204:207], v[174:177], v[8:11]
	v_mfma_f32_16x16x32_bf16 v[4:7], v[108:111], v[186:189], v[4:7]
	v_mfma_f32_16x16x32_bf16 v[0:3], v[208:211], v[186:189], v[0:3]
	v_mfma_f32_16x16x32_bf16 v[130:133], v[108:111], v[76:79], v[28:31]
	v_mfma_f32_16x16x32_bf16 v[134:137], v[208:211], v[76:79], v[24:27]
	v_mfma_f32_16x16x32_bf16 v[138:141], v[108:111], v[178:181], v[12:15]
	v_mfma_f32_16x16x32_bf16 v[142:145], v[208:211], v[178:181], v[8:11]
	s_setprio 0
	s_barrier
	s_nop 0
	ds_read_b128 v[8:11], v164 offset:32768
	ds_read_b128 v[12:15], v164 offset:33792
	ds_read_b128 v[174:177], v164 offset:34816
	ds_read_b128 v[178:181], v164 offset:35840
	ds_read_b128 v[24:27], v162 offset:32768
	ds_read_b128 v[28:31], v162 offset:33792
	ds_read_b128 v[40:43], v162 offset:34816
	ds_read_b128 v[44:47], v162 offset:35840
	ds_read_b128 v[182:185], v162 offset:36864
	ds_read_b128 v[186:189], v162 offset:37888
	ds_read_b128 v[204:207], v162 offset:38912
	ds_read_b128 v[208:211], v162 offset:39936
	s_waitcnt vmcnt(2)
	s_barrier
	s_waitcnt lgkmcnt(0)
	s_setprio 1
	s_waitcnt lgkmcnt(0)
	v_mfma_f32_16x16x32_bf16 v[72:75], v[8:11], v[24:27], v[124:127]
	v_mfma_f32_16x16x32_bf16 v[124:127], v[12:15], v[28:31], v[72:75]
	v_mfma_f32_16x16x32_bf16 v[72:75], v[174:177], v[24:27], v[120:123]
	v_mfma_f32_16x16x32_bf16 v[120:123], v[178:181], v[28:31], v[72:75]
	v_mfma_f32_16x16x32_bf16 v[72:75], v[8:11], v[40:43], v[116:119]
	v_mfma_f32_16x16x32_bf16 v[108:111], v[12:15], v[44:47], v[72:75]
	v_mfma_f32_16x16x32_bf16 v[72:75], v[174:177], v[40:43], v[112:115]
	v_mfma_f32_16x16x32_bf16 v[104:107], v[178:181], v[44:47], v[72:75]
	v_mfma_f32_16x16x32_bf16 v[72:75], v[8:11], v[182:185], v[196:199]
	v_mfma_f32_16x16x32_bf16 v[92:95], v[12:15], v[186:189], v[72:75]
	v_mfma_f32_16x16x32_bf16 v[72:75], v[174:177], v[182:185], v[200:203]
	v_mfma_f32_16x16x32_bf16 v[88:91], v[178:181], v[186:189], v[72:75]
	v_mfma_f32_16x16x32_bf16 v[72:75], v[8:11], v[204:207], v[100:103]
	v_mfma_f32_16x16x32_bf16 v[76:79], v[12:15], v[208:211], v[72:75]
	v_mfma_f32_16x16x32_bf16 v[72:75], v[174:177], v[204:207], v[96:99]
	v_mfma_f32_16x16x32_bf16 v[72:75], v[178:181], v[208:211], v[72:75]
	s_setprio 0
	s_barrier
	ds_read_b128 v[194:197], v164 offset:49152
	ds_read_b128 v[198:201], v164 offset:50176
	ds_read_b128 v[220:223], v164 offset:51200
	ds_read_b128 v[224:227], v164 offset:52224
	s_waitcnt vmcnt(0)
	s_barrier
	s_waitcnt lgkmcnt(0)
	s_setprio 1
	s_waitcnt lgkmcnt(0)
	v_mfma_f32_16x16x32_bf16 v[96:99], v[194:197], v[24:27], v[212:215]
	v_mfma_f32_16x16x32_bf16 v[24:27], v[220:223], v[24:27], v[158:161]
	v_mfma_f32_16x16x32_bf16 v[112:115], v[224:227], v[28:31], v[24:27]
	v_mfma_f32_16x16x32_bf16 v[24:27], v[194:197], v[40:43], v[84:87]
	v_mfma_f32_16x16x32_bf16 v[100:103], v[198:201], v[44:47], v[24:27]
	v_mfma_f32_16x16x32_bf16 v[24:27], v[220:223], v[40:43], v[80:83]
	v_mfma_f32_16x16x32_bf16 v[116:119], v[198:201], v[28:31], v[96:99]
	v_mfma_f32_16x16x32_bf16 v[96:99], v[224:227], v[44:47], v[24:27]
	v_mfma_f32_16x16x32_bf16 v[24:27], v[194:197], v[182:185], v[166:169]
	v_mfma_f32_16x16x32_bf16 v[84:87], v[198:201], v[186:189], v[24:27]
	v_mfma_f32_16x16x32_bf16 v[24:27], v[220:223], v[182:185], v[170:173]
	v_mfma_f32_16x16x32_bf16 v[80:83], v[224:227], v[186:189], v[24:27]
	v_mfma_f32_16x16x32_bf16 v[24:27], v[194:197], v[204:207], v[68:71]
	v_mfma_f32_16x16x32_bf16 v[68:71], v[198:201], v[208:211], v[24:27]
	v_mfma_f32_16x16x32_bf16 v[24:27], v[220:223], v[204:207], v[64:67]
	v_mfma_f32_16x16x32_bf16 v[64:67], v[224:227], v[208:211], v[24:27]
	s_setprio 0
	s_barrier
	ds_read_b128 v[158:161], v162 offset:49152
	ds_read_b128 v[164:167], v162 offset:50176
	ds_read_b128 v[168:171], v162 offset:51200
	ds_read_b128 v[182:185], v162 offset:52224
	ds_read_b128 v[186:189], v162 offset:53248
	ds_read_b128 v[202:205], v162 offset:54272
	ds_read_b128 v[206:209], v162 offset:55296
	ds_read_b128 v[210:213], v162 offset:56320
	s_barrier
	s_waitcnt lgkmcnt(0)
	s_setprio 1
	s_waitcnt lgkmcnt(0)
	v_mfma_f32_16x16x32_bf16 v[24:27], v[8:11], v[158:161], v[60:63]
	v_mfma_f32_16x16x32_bf16 v[60:63], v[12:15], v[164:167], v[24:27]
	v_mfma_f32_16x16x32_bf16 v[24:27], v[174:177], v[158:161], v[56:59]
	v_mfma_f32_16x16x32_bf16 v[56:59], v[178:181], v[164:167], v[24:27]
	v_mfma_f32_16x16x32_bf16 v[24:27], v[8:11], v[168:171], v[52:55]
	v_mfma_f32_16x16x32_bf16 v[44:47], v[12:15], v[182:185], v[24:27]
	v_mfma_f32_16x16x32_bf16 v[24:27], v[174:177], v[168:171], v[48:51]
	v_mfma_f32_16x16x32_bf16 v[40:43], v[178:181], v[182:185], v[24:27]
	v_mfma_f32_16x16x32_bf16 v[24:27], v[8:11], v[186:189], v[190:193]
	v_mfma_f32_16x16x32_bf16 v[8:11], v[8:11], v[206:209], v[36:39]
	v_mfma_f32_16x16x32_bf16 v[28:31], v[12:15], v[202:205], v[24:27]
	v_mfma_f32_16x16x32_bf16 v[24:27], v[174:177], v[186:189], v[216:219]
	v_mfma_f32_16x16x32_bf16 v[12:15], v[12:15], v[210:213], v[8:11]
	v_mfma_f32_16x16x32_bf16 v[8:11], v[174:177], v[206:209], v[32:35]
	v_mfma_f32_16x16x32_bf16 v[24:27], v[178:181], v[202:205], v[24:27]
	v_mfma_f32_16x16x32_bf16 v[8:11], v[178:181], v[210:213], v[8:11]
	s_setprio 0
	s_setprio 1
	v_mfma_f32_16x16x32_bf16 v[32:35], v[194:197], v[158:161], v[130:133]
	v_mfma_f32_16x16x32_bf16 v[52:55], v[198:201], v[164:167], v[32:35]
	v_mfma_f32_16x16x32_bf16 v[32:35], v[220:223], v[158:161], v[134:137]
	v_mfma_f32_16x16x32_bf16 v[16:19], v[220:223], v[168:171], v[16:19]
	v_mfma_f32_16x16x32_bf16 v[48:51], v[224:227], v[164:167], v[32:35]
	v_mfma_f32_16x16x32_bf16 v[20:23], v[194:197], v[168:171], v[20:23]
	v_mfma_f32_16x16x32_bf16 v[32:35], v[224:227], v[182:185], v[16:19]
	v_mfma_f32_16x16x32_bf16 v[16:19], v[194:197], v[186:189], v[138:141]
	v_mfma_f32_16x16x32_bf16 v[36:39], v[198:201], v[182:185], v[20:23]
	v_mfma_f32_16x16x32_bf16 v[20:23], v[198:201], v[202:205], v[16:19]
	v_mfma_f32_16x16x32_bf16 v[16:19], v[220:223], v[186:189], v[142:145]
	v_mfma_f32_16x16x32_bf16 v[4:7], v[194:197], v[206:209], v[4:7]
	v_mfma_f32_16x16x32_bf16 v[0:3], v[220:223], v[206:209], v[0:3]
	v_mfma_f32_16x16x32_bf16 v[16:19], v[224:227], v[202:205], v[16:19]
	v_mfma_f32_16x16x32_bf16 v[4:7], v[198:201], v[210:213], v[4:7]
	v_mfma_f32_16x16x32_bf16 v[0:3], v[224:227], v[210:213], v[0:3]
	s_setprio 0
	s_movk_i32 s2, 0x100
	v_cmp_gt_u32_e32 vcc, s2, v157
	s_barrier
	s_and_saveexec_b64 s[2:3], vcc
	s_cbranch_execz .LBB0_190
	s_barrier
